# grid barrier release flattened: non-leader WGs spin on the top generation word directly (XCD generation hop removed), on top of v73
# speedup vs baseline: 1.0030x; 1.0000x over previous
; __device__ __forceinline__ unsigned xb_ld(unsigned* p)              { return __hip_atomic_load(p, __ATOMIC_RELAXED, __HIP_MEMORY_SCOPE_AGENT); }
; __device__ __forceinline__ unsigned xb_add(unsigned* p, unsigned v) { return __hip_atomic_fetch_add(p, v, __ATOMIC_RELAXED, __HIP_MEMORY_SCOPE_AGENT); }
; #define XB_SPIN(cond, bar) do { unsigned _sp = 0; while (cond) { __builtin_amdgcn_s_sleep(1); \
;     if ((++_sp & 255u) == 0u) { if (xb_ld(&(bar)[XB_TMO])) break; if (_sp > XB_SPIN_CAP) { atomicAdd(&(bar)[XB_TMO], 1u); break; } } } } while (0)
; __device__ __forceinline__ void xcd_barrier(const XcdBarrier& b) {
;     ...
;     unsigned nloc = b.st[0], nx = b.st[1];
;     if (nloc == 0u) { xcd_barrier_complete(bar, b.x, nloc, nx); b.st[0] = nloc; b.st[1] = nx; }
;     const unsigned old = xb_add(&bar[XB_XSUB(b.x)], 1u);
;     const unsigned gen = old / nloc;
;     if (old + 1u == (gen + 1u) * nloc) {
;       __builtin_amdgcn_fence(__ATOMIC_RELEASE, "agent");
;       asm volatile("s_waitcnt vmcnt(0)" ::: "memory");
;       const unsigned og = xb_add(&bar[XB_TOP], 1u);
;       const unsigned tg = og / nx;
;       if (og + 1u == (tg + 1u) * nx) xb_add(&bar[XB_TOPGEN], 1u);
;       else XB_SPIN(xb_ld(&bar[XB_TOPGEN]) == tg, bar);
;       __builtin_amdgcn_fence(__ATOMIC_ACQUIRE, "agent");
;       xb_add(&bar[XB_XGEN(b.x)], 1u);
;       asm volatile("s_waitcnt vmcnt(0)" ::: "memory");
;     } else {
;       XB_SPIN(xb_ld(&bar[XB_XGEN(b.x)]) == gen, bar);
.LBB0_161:
	s_or_b64 exec, exec, s[34:35]
	v_cvt_f32_u32_e32 v4, v2
	s_waitcnt vmcnt(0)
	v_readfirstlane_b32 s6, v3
	v_sub_u32_e32 v3, 0, v2
	v_rcp_iflag_f32_e32 v4, v4
	v_add_u32_e32 v5, s6, v1
	v_mul_f32_e32 v4, 0x4f7ffffe, v4
	v_cvt_u32_f32_e32 v4, v4
	v_mul_lo_u32 v1, v3, v4
	v_mul_hi_u32 v1, v4, v1
	v_add_u32_e32 v1, v4, v1
	v_mul_hi_u32 v1, v5, v1
	v_mul_lo_u32 v3, v1, v2
	v_sub_u32_e32 v3, v5, v3
	v_add_u32_e32 v4, 1, v1
	v_cmp_ge_u32_e32 vcc, v3, v2
	s_nop 1
	v_cndmask_b32_e32 v1, v1, v4, vcc
	v_sub_u32_e32 v4, v3, v2
	v_cndmask_b32_e32 v3, v3, v4, vcc
	v_add_u32_e32 v4, 1, v1
	v_cmp_ge_u32_e32 vcc, v3, v2
	v_add_u32_e32 v3, 1, v5
	s_nop 0
	v_cndmask_b32_e32 v1, v1, v4, vcc
	v_mul_lo_u32 v4, v2, v1
	v_add_u32_e32 v2, v4, v2
	v_cmp_ne_u32_e32 vcc, v3, v2
	s_and_saveexec_b64 s[6:7], vcc
	s_xor_b64 s[34:35], exec, s[6:7]
	s_cbranch_execz .LBB0_175
	v_readlane_b32 s6, v251, 57
	v_readlane_b32 s7, v251, 58
	s_waitcnt lgkmcnt(0)
	s_nop 3
	global_load_dword v0, v161, s[6:7] sc1
	s_waitcnt vmcnt(0)
	v_cmp_eq_u32_e32 vcc, v0, v1
	s_and_saveexec_b64 s[36:37], vcc
	s_cbranch_execz .LBB0_174
	s_mov_b32 s6, 1
	s_mov_b64 s[38:39], 0
	s_branch .LBB0_165

; __device__ __forceinline__ unsigned xb_ld(unsigned* p)              { return __hip_atomic_load(p, __ATOMIC_RELAXED, __HIP_MEMORY_SCOPE_AGENT); }
; #define XB_SPIN(cond, bar) do { unsigned _sp = 0; while (cond) { __builtin_amdgcn_s_sleep(1); \
;     if ((++_sp & 255u) == 0u) { if (xb_ld(&(bar)[XB_TMO])) break; if (_sp > XB_SPIN_CAP) { atomicAdd(&(bar)[XB_TMO], 1u); break; } } } } while (0)
; __device__ __forceinline__ void xcd_barrier(const XcdBarrier& b) {
;     ...
;       XB_SPIN(xb_ld(&bar[XB_XGEN(b.x)]) == gen, bar);
.LBB0_169:
	v_readlane_b32 s12, v251, 57
	v_readlane_b32 s13, v251, 58
	s_add_i32 s6, s6, 1
	s_mov_b64 s[44:45], -1
	s_nop 2
	global_load_dword v0, v161, s[12:13] sc1
	s_waitcnt vmcnt(0)
	v_cmp_ne_u32_e32 vcc, v0, v1
	s_orn2_b64 s[42:43], vcc, exec
	s_branch .LBB0_164

; __device__ __forceinline__ unsigned xb_add(unsigned* p, unsigned v) { return __hip_atomic_fetch_add(p, v, __ATOMIC_RELAXED, __HIP_MEMORY_SCOPE_AGENT); }
; __device__ __forceinline__ void xcd_barrier(const XcdBarrier& b) {
;     ...
;       __builtin_amdgcn_fence(__ATOMIC_ACQUIRE, "agent");
;       xb_add(&bar[XB_XGEN(b.x)], 1u);
;       asm volatile("s_waitcnt vmcnt(0)" ::: "memory");
.LBB0_192:
	s_or_b64 exec, exec, s[34:35]
	s_mov_b64 s[34:35], exec
	v_mbcnt_lo_u32_b32 v0, s34, 0
	v_mbcnt_hi_u32_b32 v0, s35, v0
	v_cmp_eq_u32_e32 vcc, 0, v0
	s_waitcnt vmcnt(0)
	buffer_inv sc1
	s_and_saveexec_b64 s[36:37], vcc
	s_cbranch_execz .LBB0_194
	s_bcnt1_i32_b64 s6, s[34:35]
	v_mov_b32_e32 v0, s6
	v_readlane_b32 s6, v251, 53
	v_readlane_b32 s7, v251, 54
	s_nop 4
.LBB0_194:
	s_or_b64 exec, exec, s[36:37]
	s_waitcnt vmcnt(0)

; __device__ __forceinline__ unsigned xb_add(unsigned* p, unsigned v) { return __hip_atomic_fetch_add(p, v, __ATOMIC_RELAXED, __HIP_MEMORY_SCOPE_AGENT); }
; __device__ __forceinline__ void xcd_barrier(const XcdBarrier& b) {
;     ...
;       __builtin_amdgcn_fence(__ATOMIC_ACQUIRE, "agent");
;       xb_add(&bar[XB_XGEN(b.x)], 1u);
;       asm volatile("s_waitcnt vmcnt(0)" ::: "memory");
.LBB0_262:
	s_or_b64 exec, exec, s[34:35]
	s_mov_b64 s[34:35], exec
	v_mbcnt_lo_u32_b32 v0, s34, 0
	v_mbcnt_hi_u32_b32 v0, s35, v0
	v_cmp_eq_u32_e32 vcc, 0, v0
	s_waitcnt vmcnt(0)
	buffer_inv sc1
	s_and_saveexec_b64 s[36:37], vcc
	s_cbranch_execz .LBB0_264
	s_bcnt1_i32_b64 s6, s[34:35]
	v_mov_b32_e32 v0, s6
	v_readlane_b32 s6, v251, 53
	v_readlane_b32 s7, v251, 54
	s_nop 4
.LBB0_264:
	s_or_b64 exec, exec, s[36:37]
	s_waitcnt vmcnt(0)

; __device__ __forceinline__ unsigned xb_add(unsigned* p, unsigned v) { return __hip_atomic_fetch_add(p, v, __ATOMIC_RELAXED, __HIP_MEMORY_SCOPE_AGENT); }
; __device__ __forceinline__ void xcd_barrier(const XcdBarrier& b) {
;     ...
;       __builtin_amdgcn_fence(__ATOMIC_ACQUIRE, "agent");
;       xb_add(&bar[XB_XGEN(b.x)], 1u);
;       asm volatile("s_waitcnt vmcnt(0)" ::: "memory");
.LBB0_350:
	s_or_b64 exec, exec, s[34:35]
	s_mov_b64 s[34:35], exec
	v_mbcnt_lo_u32_b32 v0, s34, 0
	v_mbcnt_hi_u32_b32 v0, s35, v0
	v_cmp_eq_u32_e32 vcc, 0, v0
	s_waitcnt vmcnt(0)
	buffer_inv sc1
	s_and_saveexec_b64 s[36:37], vcc
	s_cbranch_execz .LBB0_352
	s_bcnt1_i32_b64 s6, s[34:35]
	v_mov_b32_e32 v0, s6
	v_readlane_b32 s6, v251, 53
	v_readlane_b32 s7, v251, 54
	s_nop 4
.LBB0_352:
	s_or_b64 exec, exec, s[36:37]
	s_waitcnt vmcnt(0)

; __device__ __forceinline__ unsigned xb_add(unsigned* p, unsigned v) { return __hip_atomic_fetch_add(p, v, __ATOMIC_RELAXED, __HIP_MEMORY_SCOPE_AGENT); }
; __device__ __forceinline__ void xcd_barrier(const XcdBarrier& b) {
;     ...
;       __builtin_amdgcn_fence(__ATOMIC_ACQUIRE, "agent");
;       xb_add(&bar[XB_XGEN(b.x)], 1u);
;       asm volatile("s_waitcnt vmcnt(0)" ::: "memory");
.LBB0_424:
	s_or_b64 exec, exec, s[34:35]
	s_mov_b64 s[34:35], exec
	v_mbcnt_lo_u32_b32 v0, s34, 0
	v_mbcnt_hi_u32_b32 v0, s35, v0
	v_cmp_eq_u32_e32 vcc, 0, v0
	s_waitcnt vmcnt(0)
	buffer_inv sc1
	s_and_saveexec_b64 s[36:37], vcc
	s_cbranch_execz .LBB0_426
	s_bcnt1_i32_b64 s6, s[34:35]
	v_mov_b32_e32 v0, s6
	v_readlane_b32 s6, v251, 53
	v_readlane_b32 s7, v251, 54
	s_nop 4
.LBB0_426:
	s_or_b64 exec, exec, s[36:37]
	s_waitcnt vmcnt(0)

; __device__ __forceinline__ unsigned xb_ld(unsigned* p)              { return __hip_atomic_load(p, __ATOMIC_RELAXED, __HIP_MEMORY_SCOPE_AGENT); }
; __device__ __forceinline__ unsigned xb_add(unsigned* p, unsigned v) { return __hip_atomic_fetch_add(p, v, __ATOMIC_RELAXED, __HIP_MEMORY_SCOPE_AGENT); }
; #define XB_SPIN(cond, bar) do { unsigned _sp = 0; while (cond) { __builtin_amdgcn_s_sleep(1); \
;     if ((++_sp & 255u) == 0u) { if (xb_ld(&(bar)[XB_TMO])) break; if (_sp > XB_SPIN_CAP) { atomicAdd(&(bar)[XB_TMO], 1u); break; } } } } while (0)
; __device__ __forceinline__ void xcd_barrier(const XcdBarrier& b) {
;     ...
;     unsigned nloc = b.st[0], nx = b.st[1];
;     if (nloc == 0u) { xcd_barrier_complete(bar, b.x, nloc, nx); b.st[0] = nloc; b.st[1] = nx; }
;     const unsigned old = xb_add(&bar[XB_XSUB(b.x)], 1u);
;     const unsigned gen = old / nloc;
;     if (old + 1u == (gen + 1u) * nloc) {
;       __builtin_amdgcn_fence(__ATOMIC_RELEASE, "agent");
;       asm volatile("s_waitcnt vmcnt(0)" ::: "memory");
;       const unsigned og = xb_add(&bar[XB_TOP], 1u);
;       const unsigned tg = og / nx;
;       if (og + 1u == (tg + 1u) * nx) xb_add(&bar[XB_TOPGEN], 1u);
;       else XB_SPIN(xb_ld(&bar[XB_TOPGEN]) == tg, bar);
;       __builtin_amdgcn_fence(__ATOMIC_ACQUIRE, "agent");
;       xb_add(&bar[XB_XGEN(b.x)], 1u);
;       asm volatile("s_waitcnt vmcnt(0)" ::: "memory");
;     } else {
;       XB_SPIN(xb_ld(&bar[XB_XGEN(b.x)]) == gen, bar);
.LBB0_471:
	s_or_b64 exec, exec, s[34:35]
	v_cvt_f32_u32_e32 v4, v2
	s_waitcnt vmcnt(0)
	v_readfirstlane_b32 s6, v3
	v_sub_u32_e32 v3, 0, v2
	v_rcp_iflag_f32_e32 v4, v4
	v_add_u32_e32 v5, s6, v1
	v_mul_f32_e32 v4, 0x4f7ffffe, v4
	v_cvt_u32_f32_e32 v4, v4
	v_mul_lo_u32 v1, v3, v4
	v_mul_hi_u32 v1, v4, v1
	v_add_u32_e32 v1, v4, v1
	v_mul_hi_u32 v1, v5, v1
	v_mul_lo_u32 v3, v1, v2
	v_sub_u32_e32 v3, v5, v3
	v_add_u32_e32 v4, 1, v1
	v_cmp_ge_u32_e32 vcc, v3, v2
	s_nop 1
	v_cndmask_b32_e32 v1, v1, v4, vcc
	v_sub_u32_e32 v4, v3, v2
	v_cndmask_b32_e32 v3, v3, v4, vcc
	v_add_u32_e32 v4, 1, v1
	v_cmp_ge_u32_e32 vcc, v3, v2
	v_add_u32_e32 v3, 1, v5
	s_nop 0
	v_cndmask_b32_e32 v1, v1, v4, vcc
	v_mul_lo_u32 v4, v2, v1
	v_add_u32_e32 v2, v4, v2
	v_cmp_ne_u32_e32 vcc, v3, v2
	s_and_saveexec_b64 s[6:7], vcc
	s_xor_b64 s[34:35], exec, s[6:7]
	s_cbranch_execz .LBB0_485
	v_readlane_b32 s6, v251, 57
	v_readlane_b32 s7, v251, 58
	s_waitcnt lgkmcnt(0)
	s_nop 3
	global_load_dword v0, v161, s[6:7] sc1
	s_waitcnt vmcnt(0)
	v_cmp_eq_u32_e32 vcc, v0, v1
	s_and_saveexec_b64 s[36:37], vcc
	s_cbranch_execz .LBB0_484
	s_mov_b32 s6, 1
	s_mov_b64 s[42:43], 0
	s_branch .LBB0_475

; __device__ __forceinline__ unsigned xb_ld(unsigned* p)              { return __hip_atomic_load(p, __ATOMIC_RELAXED, __HIP_MEMORY_SCOPE_AGENT); }
; #define XB_SPIN(cond, bar) do { unsigned _sp = 0; while (cond) { __builtin_amdgcn_s_sleep(1); \
;     if ((++_sp & 255u) == 0u) { if (xb_ld(&(bar)[XB_TMO])) break; if (_sp > XB_SPIN_CAP) { atomicAdd(&(bar)[XB_TMO], 1u); break; } } } } while (0)
; __device__ __forceinline__ void xcd_barrier(const XcdBarrier& b) {
;     ...
;       XB_SPIN(xb_ld(&bar[XB_XGEN(b.x)]) == gen, bar);
.LBB0_479:
	v_readlane_b32 s12, v251, 57
	v_readlane_b32 s13, v251, 58
	s_add_i32 s6, s6, 1
	s_mov_b64 s[38:39], -1
	s_nop 2
	global_load_dword v0, v161, s[12:13] sc1
	s_waitcnt vmcnt(0)
	v_cmp_ne_u32_e32 vcc, v0, v1
	s_orn2_b64 s[48:49], vcc, exec
	s_branch .LBB0_474

; __device__ __forceinline__ unsigned xb_add(unsigned* p, unsigned v) { return __hip_atomic_fetch_add(p, v, __ATOMIC_RELAXED, __HIP_MEMORY_SCOPE_AGENT); }
; __device__ __forceinline__ void xcd_barrier(const XcdBarrier& b) {
;     ...
;       __builtin_amdgcn_fence(__ATOMIC_ACQUIRE, "agent");
;       xb_add(&bar[XB_XGEN(b.x)], 1u);
;       asm volatile("s_waitcnt vmcnt(0)" ::: "memory");
.LBB0_502:
	s_or_b64 exec, exec, s[34:35]
	s_mov_b64 s[34:35], exec
	v_mbcnt_lo_u32_b32 v0, s34, 0
	v_mbcnt_hi_u32_b32 v0, s35, v0
	v_cmp_eq_u32_e32 vcc, 0, v0
	s_waitcnt vmcnt(0)
	buffer_inv sc1
	s_and_saveexec_b64 s[36:37], vcc
	s_cbranch_execz .LBB0_504
	s_bcnt1_i32_b64 s6, s[34:35]
	v_mov_b32_e32 v0, s6
	v_readlane_b32 s6, v251, 53
	v_readlane_b32 s7, v251, 54
	s_nop 4
.LBB0_504:
	s_or_b64 exec, exec, s[36:37]
	s_waitcnt vmcnt(0)

; __device__ __forceinline__ unsigned xb_ld(unsigned* p)              { return __hip_atomic_load(p, __ATOMIC_RELAXED, __HIP_MEMORY_SCOPE_AGENT); }
; #define XB_SPIN(cond, bar) do { unsigned _sp = 0; while (cond) { __builtin_amdgcn_s_sleep(1); \
;     if ((++_sp & 255u) == 0u) { if (xb_ld(&(bar)[XB_TMO])) break; if (_sp > XB_SPIN_CAP) { atomicAdd(&(bar)[XB_TMO], 1u); break; } } } } while (0)
; __device__ __forceinline__ void xcd_barrier(const XcdBarrier& b) {
;     ...
;       XB_SPIN(xb_ld(&bar[XB_XGEN(b.x)]) == gen, bar);
.LBB0_593:
	v_readlane_b32 s12, v251, 57
	v_readlane_b32 s13, v251, 58
	s_add_i32 s6, s6, 1
	s_mov_b64 s[48:49], -1
	s_nop 2
	global_load_dword v0, v161, s[12:13] sc1
	s_waitcnt vmcnt(0)
	v_cmp_ne_u32_e32 vcc, v0, v1
	s_orn2_b64 s[44:45], vcc, exec
	s_branch .LBB0_588

; __device__ __forceinline__ unsigned xb_add(unsigned* p, unsigned v) { return __hip_atomic_fetch_add(p, v, __ATOMIC_RELAXED, __HIP_MEMORY_SCOPE_AGENT); }
; __device__ __forceinline__ void xcd_barrier(const XcdBarrier& b) {
;     ...
;       __builtin_amdgcn_fence(__ATOMIC_ACQUIRE, "agent");
;       xb_add(&bar[XB_XGEN(b.x)], 1u);
;       asm volatile("s_waitcnt vmcnt(0)" ::: "memory");
.LBB0_616:
	s_or_b64 exec, exec, s[34:35]
	s_mov_b64 s[34:35], exec
	v_mbcnt_lo_u32_b32 v0, s34, 0
	v_mbcnt_hi_u32_b32 v0, s35, v0
	v_cmp_eq_u32_e32 vcc, 0, v0
	s_waitcnt vmcnt(0)
	buffer_inv sc1
	s_and_saveexec_b64 s[36:37], vcc
	s_cbranch_execz .LBB0_618
	s_bcnt1_i32_b64 s6, s[34:35]
	v_mov_b32_e32 v0, s6
	v_readlane_b32 s6, v251, 53
	v_readlane_b32 s7, v251, 54
	s_nop 4
.LBB0_618:
	s_or_b64 exec, exec, s[36:37]
	s_waitcnt vmcnt(0)

; __device__ __forceinline__ unsigned xb_add(unsigned* p, unsigned v) { return __hip_atomic_fetch_add(p, v, __ATOMIC_RELAXED, __HIP_MEMORY_SCOPE_AGENT); }
; __device__ __forceinline__ void xcd_barrier(const XcdBarrier& b) {
;     ...
;       __builtin_amdgcn_fence(__ATOMIC_ACQUIRE, "agent");
;       xb_add(&bar[XB_XGEN(b.x)], 1u);
;       asm volatile("s_waitcnt vmcnt(0)" ::: "memory");
.LBB0_690:
	s_or_b64 exec, exec, s[34:35]
	s_mov_b64 s[34:35], exec
	v_mbcnt_lo_u32_b32 v0, s34, 0
	v_mbcnt_hi_u32_b32 v0, s35, v0
	v_cmp_eq_u32_e32 vcc, 0, v0
	s_waitcnt vmcnt(0)
	buffer_inv sc1
	s_and_saveexec_b64 s[36:37], vcc
	s_cbranch_execz .LBB0_692
	s_bcnt1_i32_b64 s6, s[34:35]
	v_mov_b32_e32 v0, s6
	v_readlane_b32 s6, v251, 53
	v_readlane_b32 s7, v251, 54
	s_nop 4
.LBB0_692:
	s_or_b64 exec, exec, s[36:37]
	s_waitcnt vmcnt(0)

; __device__ __forceinline__ unsigned xb_add(unsigned* p, unsigned v) { return __hip_atomic_fetch_add(p, v, __ATOMIC_RELAXED, __HIP_MEMORY_SCOPE_AGENT); }
; __device__ __forceinline__ void xcd_barrier(const XcdBarrier& b) {
;     ...
;       __builtin_amdgcn_fence(__ATOMIC_ACQUIRE, "agent");
;       xb_add(&bar[XB_XGEN(b.x)], 1u);
;       asm volatile("s_waitcnt vmcnt(0)" ::: "memory");
.LBB0_764:
	s_or_b64 exec, exec, s[34:35]
	s_mov_b64 s[34:35], exec
	v_mbcnt_lo_u32_b32 v0, s34, 0
	v_mbcnt_hi_u32_b32 v0, s35, v0
	v_cmp_eq_u32_e32 vcc, 0, v0
	s_waitcnt vmcnt(0)
	buffer_inv sc1
	s_and_saveexec_b64 s[36:37], vcc
	s_cbranch_execz .LBB0_766
	s_bcnt1_i32_b64 s6, s[34:35]
	v_mov_b32_e32 v0, s6
	v_readlane_b32 s6, v251, 53
	v_readlane_b32 s7, v251, 54
	s_nop 4
.LBB0_766:
	s_or_b64 exec, exec, s[36:37]
	s_waitcnt vmcnt(0)

; __device__ __forceinline__ unsigned xb_add(unsigned* p, unsigned v) { return __hip_atomic_fetch_add(p, v, __ATOMIC_RELAXED, __HIP_MEMORY_SCOPE_AGENT); }
; __device__ __forceinline__ void xcd_barrier(const XcdBarrier& b) {
;     ...
;       __builtin_amdgcn_fence(__ATOMIC_ACQUIRE, "agent");
;       xb_add(&bar[XB_XGEN(b.x)], 1u);
;       asm volatile("s_waitcnt vmcnt(0)" ::: "memory");
.LBB0_848:
	s_or_b64 exec, exec, s[34:35]
	s_mov_b64 s[34:35], exec
	v_mbcnt_lo_u32_b32 v0, s34, 0
	v_mbcnt_hi_u32_b32 v0, s35, v0
	v_cmp_eq_u32_e32 vcc, 0, v0
	s_waitcnt vmcnt(0)
	buffer_inv sc1
	s_and_saveexec_b64 s[36:37], vcc
	s_cbranch_execz .LBB0_850
	s_bcnt1_i32_b64 s6, s[34:35]
	v_mov_b32_e32 v0, s6
	v_readlane_b32 s6, v251, 53
	v_readlane_b32 s7, v251, 54
	s_nop 4
.LBB0_850:
	s_or_b64 exec, exec, s[36:37]
	s_waitcnt vmcnt(0)

; __device__ __forceinline__ unsigned xb_add(unsigned* p, unsigned v) { return __hip_atomic_fetch_add(p, v, __ATOMIC_RELAXED, __HIP_MEMORY_SCOPE_AGENT); }
; __device__ __forceinline__ void xcd_barrier(const XcdBarrier& b) {
;     ...
;       __builtin_amdgcn_fence(__ATOMIC_ACQUIRE, "agent");
;       xb_add(&bar[XB_XGEN(b.x)], 1u);
;       asm volatile("s_waitcnt vmcnt(0)" ::: "memory");
.LBB0_944:
	s_or_b64 exec, exec, s[34:35]
	s_mov_b64 s[34:35], exec
	v_mbcnt_lo_u32_b32 v0, s34, 0
	v_mbcnt_hi_u32_b32 v0, s35, v0
	v_cmp_eq_u32_e32 vcc, 0, v0
	s_waitcnt vmcnt(0)
	buffer_inv sc1
	s_and_saveexec_b64 s[36:37], vcc
	s_cbranch_execz .LBB0_946
	s_bcnt1_i32_b64 s6, s[34:35]
	v_mov_b32_e32 v0, s6
	v_readlane_b32 s6, v251, 53
	v_readlane_b32 s7, v251, 54
	s_nop 4
.LBB0_946:
	s_or_b64 exec, exec, s[36:37]
	s_waitcnt vmcnt(0)

; __device__ __forceinline__ unsigned xb_add(unsigned* p, unsigned v) { return __hip_atomic_fetch_add(p, v, __ATOMIC_RELAXED, __HIP_MEMORY_SCOPE_AGENT); }
; __device__ __forceinline__ void xcd_barrier(const XcdBarrier& b) {
;     ...
;       __builtin_amdgcn_fence(__ATOMIC_ACQUIRE, "agent");
;       xb_add(&bar[XB_XGEN(b.x)], 1u);
;       asm volatile("s_waitcnt vmcnt(0)" ::: "memory");
.LBB0_1042:
	s_or_b64 exec, exec, s[34:35]
	s_mov_b64 s[34:35], exec
	v_mbcnt_lo_u32_b32 v0, s34, 0
	v_mbcnt_hi_u32_b32 v0, s35, v0
	v_cmp_eq_u32_e32 vcc, 0, v0
	s_waitcnt vmcnt(0)
	buffer_inv sc1
	s_and_saveexec_b64 s[36:37], vcc
	s_cbranch_execz .LBB0_1044
	s_bcnt1_i32_b64 s6, s[34:35]
	v_mov_b32_e32 v0, s6
	v_readlane_b32 s6, v251, 53
	v_readlane_b32 s7, v251, 54
	s_nop 4
.LBB0_1044:
	s_or_b64 exec, exec, s[36:37]
	s_waitcnt vmcnt(0)

; __device__ __forceinline__ unsigned xb_add(unsigned* p, unsigned v) { return __hip_atomic_fetch_add(p, v, __ATOMIC_RELAXED, __HIP_MEMORY_SCOPE_AGENT); }
; __device__ __forceinline__ void xcd_barrier(const XcdBarrier& b) {
;     ...
;       __builtin_amdgcn_fence(__ATOMIC_ACQUIRE, "agent");
;       xb_add(&bar[XB_XGEN(b.x)], 1u);
;       asm volatile("s_waitcnt vmcnt(0)" ::: "memory");
.LBB0_1126:
	s_or_b64 exec, exec, s[34:35]
	s_mov_b64 s[34:35], exec
	v_mbcnt_lo_u32_b32 v0, s34, 0
	v_mbcnt_hi_u32_b32 v0, s35, v0
	v_cmp_eq_u32_e32 vcc, 0, v0
	s_waitcnt vmcnt(0)
	buffer_inv sc1
	s_and_saveexec_b64 s[36:37], vcc
	s_cbranch_execz .LBB0_1128
	s_bcnt1_i32_b64 s6, s[34:35]
	v_mov_b32_e32 v0, s6
	v_readlane_b32 s6, v251, 53
	v_readlane_b32 s7, v251, 54
	s_nop 4
.LBB0_1128:
	s_or_b64 exec, exec, s[36:37]
	s_waitcnt vmcnt(0)

; __device__ __forceinline__ unsigned xb_add(unsigned* p, unsigned v) { return __hip_atomic_fetch_add(p, v, __ATOMIC_RELAXED, __HIP_MEMORY_SCOPE_AGENT); }
; __device__ __forceinline__ void xcd_barrier(const XcdBarrier& b) {
;     ...
;       __builtin_amdgcn_fence(__ATOMIC_ACQUIRE, "agent");
;       xb_add(&bar[XB_XGEN(b.x)], 1u);
;       asm volatile("s_waitcnt vmcnt(0)" ::: "memory");
.LBB0_1196:
	s_or_b64 exec, exec, s[34:35]
	s_mov_b64 s[34:35], exec
	v_mbcnt_lo_u32_b32 v0, s34, 0
	v_mbcnt_hi_u32_b32 v0, s35, v0
	v_cmp_eq_u32_e32 vcc, 0, v0
	s_waitcnt vmcnt(0)
	buffer_inv sc1
	s_and_saveexec_b64 s[36:37], vcc
	s_cbranch_execz .LBB0_1198
	s_bcnt1_i32_b64 s6, s[34:35]
	v_mov_b32_e32 v0, s6
	v_readlane_b32 s6, v251, 53
	v_readlane_b32 s7, v251, 54
	s_nop 4
.LBB0_1198:
	s_or_b64 exec, exec, s[36:37]
	s_waitcnt vmcnt(0)

; __device__ __forceinline__ unsigned xb_add(unsigned* p, unsigned v) { return __hip_atomic_fetch_add(p, v, __ATOMIC_RELAXED, __HIP_MEMORY_SCOPE_AGENT); }
; __device__ __forceinline__ void xcd_barrier(const XcdBarrier& b) {
;     ...
;       __builtin_amdgcn_fence(__ATOMIC_ACQUIRE, "agent");
;       xb_add(&bar[XB_XGEN(b.x)], 1u);
;       asm volatile("s_waitcnt vmcnt(0)" ::: "memory");
.LBB0_1285:
	s_bcnt1_i32_b64 s6, s[34:35]
	v_mov_b32_e32 v0, s6
	v_readlane_b32 s6, v251, 53
	v_readlane_b32 s7, v251, 54
	s_nop 4
	s_getpc_b64 s[98:99]
